# e56 + pool workgroups run their deferred in_proj tile before waiting for the P2->P3 barrier (e43)
# speedup vs baseline: 1.0017x; 1.0017x over previous
; #define SUB(i, ...) do { if (PROBE_PH == phk && PROBE_SUB == (i)) { __syncthreads(); tp0 = __builtin_amdgcn_s_memrealtime(); } __VA_ARGS__ if (PROBE_PH == phk && PROBE_SUB == (i)) { asm volatile("s_waitcnt vmcnt(0)" ::: "memory"); __syncthreads(); tp1 = __builtin_amdgcn_s_memrealtime(); } } while (0)
; __global__ void __launch_bounds__(NTHREADS, 2) mk_fwd(Args a) {
;     ...
;     PHASE(3,
;         const int ridx = vcu >> 1;
;         const int sg = ridx >> 1, sb = ridx & 1;
;         unsigned* f1 = ctl + 8192 + ridx; unsigned* f2 = f1 + 128; unsigned* f3 = f1 + 256;
;         pg8::OneUnit SZ; SZ.u.g = 0; SZ.u.pm = 16 * ((bx & 7) >> 1) + (bx >> 4); SZ.u.pn = 12 + 2 * (bx & 1) + ((bx >> 3) & 1); SZ.have = true;
;         EpiInProj EZ{(f16*)(a.ws + WS_UPOOL), (f16*)(a.ws + WS_X), (f16*)(a.ws + WS_ZS)};
;         if (!(vcu & 1)) {
;             SUB(0, ctxs_item(sg, (const f16*)(a.ws + WS_X), (const f16*)(a.ws + WS_PG), (float*)(a.ws + WS_S)); );
.LBB0_490:
	s_cmp_lt_i32 s78, 4
	s_cselect_b64 s[0:1], -1, 0
	s_and_b64 s[90:91], s[0:1], s[2:3]
	s_andn2_b64 vcc, exec, s[90:91]
	s_cbranch_vccnz .LBB0_997
	s_mov_b32 s100, 0
	s_bitcmp1_b32 s81, 0
	s_cbranch_scc0 .Lp3_tr_skip
	s_lshr_b32 s100, s81, 1
	s_cmp_lt_u32 s100, 6
	s_cbranch_scc1 .Lp3_tr_skip
	s_mov_b32 s98, s81
	s_add_i32 s81, s100, 0x80
	s_mov_b32 s20, s100
	s_mov_b32 s99, 1
	s_mov_b32 s13, 0
	s_mul_i32 s28, s53, 0x2100
	v_and_b32_e32 v212, 63, v0
	v_readlane_b32 s100, v254, 0
	v_readlane_b32 s101, v254, 1
	s_nop 3
	s_sub_u32 s100, s100, 0xc8
	s_subb_u32 s101, s101, 0
	s_add_u32 s0, s50, 0x2000000
	s_addc_u32 s1, s51, 0
	s_add_u32 s4, s50, 0x13600000
	s_addc_u32 s5, s51, 0
	s_load_dwordx2 s[40:41], s[100:101], 0x90
	s_load_dwordx2 s[44:45], s[100:101], 0xa0
	s_waitcnt lgkmcnt(0)
	s_branch .Lp1_tr_setup

; #define PG8_STAGE_A(bufoff, gbase) PG8_STAGE(bufoff, gbase, voffA, a64)
; #define PG8_STAGE_B(bufoff, bp, hb, tz) do { if (BMODE == 1 && (tz)) PG8_STAGE(bufoff, (bp) + (hb) * 4096, voffT, t64); else PG8_STAGE(bufoff, (bp) + (hb) * bhstep, voffB, b64); } while (0)
; #define PG8_WAIT_V(n) asm volatile("s_waitcnt vmcnt(" #n ")" ::: "memory")
; #define PG8_BAR __builtin_amdgcn_s_barrier()
; #define SUB(i, ...) do { if (PROBE_PH == phk && PROBE_SUB == (i)) { __syncthreads(); tp0 = __builtin_amdgcn_s_memrealtime(); } __VA_ARGS__ if (PROBE_PH == phk && PROBE_SUB == (i)) { asm volatile("s_waitcnt vmcnt(0)" ::: "memory"); __syncthreads(); tp1 = __builtin_amdgcn_s_memrealtime(); } } while (0)
; template <class CF, class Epi, class Sched, bool ALIGN_EPI, bool SP2>
; __device__ __forceinline__ void gemm_phase(LAS unsigned char* lds, const char* gA, const char* gB, const Sched& S, const Epi& E, const char* gB2 = nullptr) {
;     ...
;     const char* cA = gA + (size_t)cur.g * CF::A_G + (size_t)cur.pm * CF::A_T; const char* cB = gB + (size_t)cur.g * CF::B_G + (size_t)cur.pn * CF::B_T;
;     const char* cT = BMODE == 1 ? gB2 + (size_t)cur.g * KTG + (size_t)cur.pn * 8192 + 14336 : nullptr;
;     PG8_STAGE_B(PG8_SB(0, 0), cB, 0, false); PG8_STAGE_B(PG8_SB(0, 1), cB, 1, false); PG8_STAGE_A(PG8_SA(0, 0), cA); PG8_STAGE_A(PG8_SA(0, 1), cA + ahstep);
;     if (wr == 1) PG8_BAR;
;     PG8_WAIT_V(2); PG8_BAR;
;     PG8_STAGE_B(PG8_SB(1, 0), cB + bkstep, 0, false); PG8_STAGE_A(PG8_SA(1, 0), cA + akstep); PG8_STAGE_B(PG8_SB(1, 1), cB + bkstep, 1, false);
;     PG8_WAIT_V(6); PG8_BAR;
; __global__ void __launch_bounds__(NTHREADS, 2) mk_fwd(Args a) {
;     ...
;             SUB(7, pg8::gemm_phase<CfgDense2048, EpiInProj, pg8::OneUnit, true, true>(lds, (const char*)(a.ws + WS_H), (const char*)(a.ws + WS_WIN), SZ, EZ); );
.Lp3_pool_tile:
	v_readfirstlane_b32 s0, v0
	s_lshr_b32 s12, s0, 6
	s_ashr_i32 s31, s30, 31
	s_lshr_b32 s13, s0, 8
	s_lshl_b32 s70, s12, 10
	s_lshl_b64 s[20:21], s[30:31], 20
	s_add_u32 s1, s50, s20
	v_lshrrev_b32_e32 v1, 5, v0
	v_bfe_u32 v2, v0, 2, 2
	s_addc_u32 s3, s51, s21
	v_and_or_b32 v1, v1, 4, v2
	v_lshrrev_b32_e32 v2, 3, v0
	v_lshrrev_b32_e32 v4, 1, v0
	s_add_u32 s2, s1, 0x6100000
	v_and_b32_e32 v3, 32, v2
	v_and_b32_e32 v215, 24, v4
	s_addc_u32 s3, s3, 0
	s_lshl_b32 s1, s29, 20
	v_or3_b32 v216, v1, v3, v215
	v_lshlrev_b32_e32 v213, 4, v0
	v_and_b32_e32 v1, 32, v0
	s_add_u32 s1, s50, s1
	v_bitop3_b32 v6, v213, v1, 48 bitop3:0x6c
	v_and_b32_e32 v7, 64, v0
	s_addc_u32 s5, s51, 0
	v_or_b32_e32 v214, v6, v7
	s_add_u32 s4, s1, 0x400000
	v_lshl_or_b32 v130, v216, 12, v214
	v_bfe_u32 v8, v0, 2, 4
	s_addc_u32 s5, s5, 0
	v_mov_b32_e32 v131, 0
	s_add_i32 s1, s70, 0
	v_and_or_b32 v219, v2, 48, v8
	v_lshl_add_u64 v[2:3], s[4:5], 0, v[130:131]
	s_add_i32 m0, s1, 0x10000
	s_mov_b64 s[6:7], 0x40000
	global_load_lds_dwordx4 v130, s[4:5]
	v_lshl_add_u64 v[4:5], v[2:3], 0, s[6:7]
	s_add_i32 m0, s1, 0x12000
	s_mov_b64 s[8:9], 0x80000
	global_load_lds_dwordx4 v[4:5], off
	v_lshl_add_u64 v[4:5], v[2:3], 0, s[8:9]
	s_add_i32 m0, s1, 0x14000
	s_mov_b64 s[10:11], 0xc0000
	v_lshl_or_b32 v132, v219, 12, v214
	global_load_lds_dwordx4 v[4:5], off
	v_lshl_add_u64 v[4:5], v[2:3], 0, s[10:11]
	s_add_i32 m0, s1, 0x16000
	v_mov_b32_e32 v133, v131
	global_load_lds_dwordx4 v[4:5], off
	v_lshl_add_u64 v[4:5], s[2:3], 0, v[132:133]
	s_mov_b32 m0, s1
	s_add_i32 s31, s1, 0x2000
	global_load_lds_dwordx4 v132, s[2:3]
	v_lshl_add_u64 v[10:11], v[4:5], 0, s[6:7]
	s_mov_b32 m0, s31
	s_add_i32 s33, s1, 0x4000
	global_load_lds_dwordx4 v[10:11], off
	v_lshl_add_u64 v[10:11], v[4:5], 0, s[8:9]
	s_mov_b32 m0, s33
	s_add_i32 s35, s1, 0x6000
	global_load_lds_dwordx4 v[10:11], off
	v_lshl_add_u64 v[10:11], v[4:5], 0, s[10:11]
	s_mov_b32 m0, s35
	s_mov_b32 s28, s81
	global_load_lds_dwordx4 v[10:11], off
	s_cmp_lg_u32 s13, 1
	s_cbranch_scc1 .LBB0_494
	s_barrier

; __device__ __forceinline__ u32x4 pack8(const f32x4 v0, const f32x4 v1) { u32x4 w; w.x = pk_f16(v0[0], v0[1]); w.y = pk_f16(v0[2], v0[3]); w.z = pk_f16(v1[0], v1[1]); w.w = pk_f16(v1[2], v1[3]); return w; }
; __device__ __forceinline__ float fast_sigmoid(float v) { return __builtin_amdgcn_rcpf(1.f + __expf(-v)); }
; __device__ __forceinline__ float silu_f(float v) { return v * fast_sigmoid(v); }
;     __device__ __forceinline__ void operator()(AccRef acc, const Unit& u, int wr, int wc, int fr, int fq) const {
;     ...
;                     else {
; #pragma unroll
;                         for (int j = 0; j < 4; ++j) { v0[j] = silu_f(v0[j]); v1[j] = silu_f(v1[j]); }
;                         *(u32x4*)(zs + (size_t)row * D + (col - PW - SW)) = pack8(v0, v1); } } }
.LBB0_498:
	v_lshl_or_b32 v131, s29, 8, v215
	v_or_b32_e32 v132, s60, v131
	v_mul_f32_e32 v131, 0xbfb8aa3b, v126
	v_mul_f32_e32 v134, 0xbfb8aa3b, v122
	v_mul_f32_e32 v135, 0xbfb8aa3b, v127
	v_exp_f32_e32 v133, v131
	v_exp_f32_e32 v134, v134
	v_exp_f32_e32 v135, v135
	v_lshl_add_u32 v130, s30, 8, v136
	v_add_f32_e32 v133, 1.0, v133
	v_add_f32_e32 v134, 1.0, v134
	v_add_f32_e32 v135, 1.0, v135
	v_mul_f32_e32 v136, 0xbfb8aa3b, v123
	v_rcp_f32_e32 v133, v133
	v_rcp_f32_e32 v134, v134
	v_rcp_f32_e32 v135, v135
	v_exp_f32_e32 v136, v136
	v_mul_f32_e32 v126, v126, v133
	v_mul_f32_e32 v122, v122, v134
	v_mul_f32_e32 v127, v127, v135
	v_add_f32_e32 v133, 1.0, v136
	v_mul_f32_e32 v134, 0xbfb8aa3b, v128
	v_mul_f32_e32 v135, 0xbfb8aa3b, v124
	v_rcp_f32_e32 v133, v133
	v_exp_f32_e32 v134, v134
	v_exp_f32_e32 v135, v135
	v_mul_f32_e32 v136, 0xbfb8aa3b, v125
	v_mul_f32_e32 v123, v123, v133
	v_add_f32_e32 v133, 1.0, v134
	v_add_f32_e32 v134, 1.0, v135
	v_mul_f32_e32 v135, 0xbfb8aa3b, v129
	v_exp_f32_e32 v136, v136
	v_exp_f32_e32 v135, v135
	v_rcp_f32_e32 v133, v133
	v_rcp_f32_e32 v134, v134
	v_add_f32_e32 v136, 1.0, v136
	v_add_f32_e32 v135, 1.0, v135
	v_rcp_f32_e32 v136, v136
	v_rcp_f32_e32 v135, v135
	v_mul_f32_e32 v128, v128, v133
	v_ashrrev_i32_e32 v131, 31, v130
	v_lshlrev_b64 v[130:131], 12, v[130:131]
	v_mul_f32_e32 v133, v124, v134
	v_mul_f32_e32 v134, v125, v136
	v_mul_f32_e32 v129, v129, v135
	v_cvt_pk_bf16_f32 v124, v126, v127
	v_cvt_pk_bf16_f32 v126, v122, v123
	v_cvt_pk_bf16_f32 v127, v133, v134
	v_lshl_add_u64 v[122:123], s[92:93], 0, v[130:131]
	v_ashrrev_i32_e32 v133, 31, v132
	v_cvt_pk_bf16_f32 v125, v128, v129
	v_lshl_add_u64 v[122:123], v[132:133], 1, v[122:123]
	v_mul_f32_e32 v128, 0xbfb8aa3b, v118
	global_store_dwordx4 v[122:123], v[124:127], off offset:-4096
	v_exp_f32_e32 v128, v128
	s_mov_b32 s2, s30
	v_mul_f32_e32 v125, 0xbfb8aa3b, v114
	v_mul_f32_e32 v126, 0xbfb8aa3b, v119
	v_exp_f32_e32 v125, v125
	v_exp_f32_e32 v126, v126
	v_add_f32_e32 v124, 1.0, v128
	v_mul_f32_e32 v127, 0xbfb8aa3b, v115
	v_add_f32_e32 v125, 1.0, v125
	v_add_f32_e32 v126, 1.0, v126
	v_rcp_f32_e32 v124, v124
	v_rcp_f32_e32 v125, v125
	v_rcp_f32_e32 v126, v126
	v_exp_f32_e32 v127, v127
	v_mul_f32_e32 v118, v118, v124
	v_mul_f32_e32 v124, v114, v125
	v_mul_f32_e32 v114, v119, v126
	v_add_f32_e32 v119, 1.0, v127
	v_mul_f32_e32 v125, 0xbfb8aa3b, v120
	v_mul_f32_e32 v126, 0xbfb8aa3b, v116
	v_rcp_f32_e32 v119, v119
	v_exp_f32_e32 v125, v125
	v_exp_f32_e32 v126, v126
	v_mul_f32_e32 v127, 0xbfb8aa3b, v117
	v_mul_f32_e32 v119, v115, v119
	v_add_f32_e32 v115, 1.0, v125
	v_add_f32_e32 v125, 1.0, v126
	v_mul_f32_e32 v126, 0xbfb8aa3b, v121
	v_exp_f32_e32 v126, v126
	v_exp_f32_e32 v127, v127
	v_rcp_f32_e32 v115, v115
	v_rcp_f32_e32 v125, v125
	v_add_f32_e32 v126, 1.0, v126
	v_rcp_f32_e32 v126, v126
	v_add_f32_e32 v127, 1.0, v127
	v_rcp_f32_e32 v127, v127
	v_mul_f32_e32 v115, v120, v115
	v_mul_f32_e32 v120, v116, v125
	v_mul_f32_e32 v116, v121, v126
	v_mul_f32_e32 v117, v117, v127
	v_cvt_pk_bf16_f32 v115, v115, v116
	v_mul_f32_e32 v116, 0xbfb8aa3b, v110
	v_cvt_pk_bf16_f32 v114, v118, v114
	v_exp_f32_e32 v118, v116
	v_cvt_pk_bf16_f32 v116, v124, v119
	v_cvt_pk_bf16_f32 v117, v120, v117
	global_store_dwordx4 v[122:123], v[114:117], off offset:-3840
	v_writelane_b32 v254, s2, 36
	s_add_u32 s0, s50, 0xa300000
	v_mul_f32_e32 v115, 0xbfb8aa3b, v106
	v_mul_f32_e32 v116, 0xbfb8aa3b, v111
	v_exp_f32_e32 v115, v115
	v_exp_f32_e32 v116, v116
	v_add_f32_e32 v114, 1.0, v118
	v_mul_f32_e32 v117, 0xbfb8aa3b, v107
	v_add_f32_e32 v115, 1.0, v115
	v_add_f32_e32 v116, 1.0, v116
	v_rcp_f32_e32 v114, v114
	v_rcp_f32_e32 v115, v115
	v_rcp_f32_e32 v116, v116
	v_exp_f32_e32 v117, v117
	v_mul_f32_e32 v110, v110, v114
	v_mul_f32_e32 v114, v106, v115
	v_mul_f32_e32 v106, v111, v116
	v_add_f32_e32 v111, 1.0, v117
	v_mul_f32_e32 v115, 0xbfb8aa3b, v112
	v_mul_f32_e32 v116, 0xbfb8aa3b, v108
	v_rcp_f32_e32 v111, v111
	v_exp_f32_e32 v115, v115
	v_exp_f32_e32 v116, v116
	v_mul_f32_e32 v117, 0xbfb8aa3b, v109
	v_mul_f32_e32 v111, v107, v111
	v_add_f32_e32 v107, 1.0, v115
	v_add_f32_e32 v115, 1.0, v116
	v_mul_f32_e32 v116, 0xbfb8aa3b, v113
	v_exp_f32_e32 v116, v116
	v_exp_f32_e32 v117, v117
	v_rcp_f32_e32 v107, v107
	v_rcp_f32_e32 v115, v115
	v_add_f32_e32 v116, 1.0, v116
	v_add_f32_e32 v117, 1.0, v117
	v_rcp_f32_e32 v116, v116
	v_rcp_f32_e32 v117, v117
	v_writelane_b32 v254, s3, 37
	v_mul_f32_e32 v107, v112, v107
	v_mul_f32_e32 v112, v108, v115
	v_mul_f32_e32 v108, v113, v116
	v_mul_f32_e32 v109, v109, v117
	v_cvt_pk_bf16_f32 v106, v110, v106
	v_mul_f32_e32 v110, 0xbfb8aa3b, v102
	s_mov_b64 s[2:3], 0x10000
	v_cvt_pk_bf16_f32 v107, v107, v108
	v_cvt_pk_bf16_f32 v108, v114, v111
	v_cvt_pk_bf16_f32 v109, v112, v109
	v_exp_f32_e32 v112, v110
	v_lshl_add_u64 v[110:111], v[122:123], 0, s[2:3]
	global_store_dwordx4 v[110:111], v[106:109], off offset:-4096
	s_mov_b64 s[2:3], 0x20000
	s_addc_u32 s1, s51, 0
	v_mul_f32_e32 v107, 0xbfb8aa3b, v98
	v_mul_f32_e32 v108, 0xbfb8aa3b, v103
	v_exp_f32_e32 v107, v107
	v_exp_f32_e32 v108, v108
	v_add_f32_e32 v106, 1.0, v112
	v_mul_f32_e32 v109, 0xbfb8aa3b, v99
	v_add_f32_e32 v107, 1.0, v107
	v_add_f32_e32 v108, 1.0, v108
	v_rcp_f32_e32 v106, v106
	v_rcp_f32_e32 v107, v107
	v_rcp_f32_e32 v108, v108
	v_exp_f32_e32 v109, v109
	v_mul_f32_e32 v102, v102, v106
	v_mul_f32_e32 v106, v98, v107
	v_mul_f32_e32 v98, v103, v108
	v_add_f32_e32 v103, 1.0, v109
	v_mul_f32_e32 v107, 0xbfb8aa3b, v104
	v_mul_f32_e32 v108, 0xbfb8aa3b, v100
	v_rcp_f32_e32 v103, v103
	v_exp_f32_e32 v107, v107
	v_exp_f32_e32 v108, v108
	v_mul_f32_e32 v109, 0xbfb8aa3b, v101
	v_mul_f32_e32 v103, v99, v103
; __device__ __forceinline__ u32x4 pack8(const f32x4 v0, const f32x4 v1) { u32x4 w; w.x = pk_f16(v0[0], v0[1]); w.y = pk_f16(v0[2], v0[3]); w.z = pk_f16(v1[0], v1[1]); w.w = pk_f16(v1[2], v1[3]); return w; }
; __device__ __forceinline__ float fast_sigmoid(float v) { return __builtin_amdgcn_rcpf(1.f + __expf(-v)); }
; __device__ __forceinline__ float silu_f(float v) { return v * fast_sigmoid(v); }
;     __device__ __forceinline__ void operator()(AccRef acc, const Unit& u, int wr, int wc, int fr, int fq) const {
;     ...
;                     else {
; #pragma unroll
;                         for (int j = 0; j < 4; ++j) { v0[j] = silu_f(v0[j]); v1[j] = silu_f(v1[j]); }
;                         *(u32x4*)(zs + (size_t)row * D + (col - PW - SW)) = pack8(v0, v1); } } }
	v_add_f32_e32 v99, 1.0, v107
	v_add_f32_e32 v107, 1.0, v108
	v_mul_f32_e32 v108, 0xbfb8aa3b, v105
	v_exp_f32_e32 v108, v108
	v_exp_f32_e32 v109, v109
	v_rcp_f32_e32 v99, v99
	v_rcp_f32_e32 v107, v107
	v_add_f32_e32 v108, 1.0, v108
	v_rcp_f32_e32 v108, v108
	v_add_f32_e32 v109, 1.0, v109
	v_rcp_f32_e32 v109, v109
	v_mul_f32_e32 v99, v104, v99
	v_mul_f32_e32 v104, v100, v107
	v_mul_f32_e32 v100, v105, v108
	v_mul_f32_e32 v101, v101, v109
	v_cvt_pk_bf16_f32 v99, v99, v100
	v_mul_f32_e32 v100, 0xbfb8aa3b, v94
	v_cvt_pk_bf16_f32 v98, v102, v98
	v_exp_f32_e32 v102, v100
	v_cvt_pk_bf16_f32 v100, v106, v103
	v_cvt_pk_bf16_f32 v101, v104, v101
	global_store_dwordx4 v[110:111], v[98:101], off offset:-3840
	s_lshl_b32 s31, s34, 2
	s_and_b32 s35, s31, 0x80
	v_mul_f32_e32 v99, 0xbfb8aa3b, v90
	v_mul_f32_e32 v100, 0xbfb8aa3b, v95
	v_exp_f32_e32 v99, v99
	v_exp_f32_e32 v100, v100
	v_add_f32_e32 v98, 1.0, v102
	v_mul_f32_e32 v101, 0xbfb8aa3b, v91
	v_add_f32_e32 v99, 1.0, v99
	v_add_f32_e32 v100, 1.0, v100
	v_rcp_f32_e32 v98, v98
	v_rcp_f32_e32 v99, v99
	v_rcp_f32_e32 v100, v100
	v_exp_f32_e32 v101, v101
	v_mul_f32_e32 v94, v94, v98
	v_mul_f32_e32 v98, v90, v99
	v_mul_f32_e32 v90, v95, v100
	v_add_f32_e32 v95, 1.0, v101
	v_mul_f32_e32 v99, 0xbfb8aa3b, v96
	v_mul_f32_e32 v100, 0xbfb8aa3b, v92
	v_rcp_f32_e32 v95, v95
	v_exp_f32_e32 v99, v99
	v_exp_f32_e32 v100, v100
	v_mul_f32_e32 v101, 0xbfb8aa3b, v93
	v_mul_f32_e32 v95, v91, v95
	v_add_f32_e32 v91, 1.0, v99
	v_add_f32_e32 v99, 1.0, v100
	v_mul_f32_e32 v100, 0xbfb8aa3b, v97
	v_exp_f32_e32 v100, v100
	v_exp_f32_e32 v101, v101
	v_rcp_f32_e32 v91, v91
	v_rcp_f32_e32 v99, v99
	v_add_f32_e32 v100, 1.0, v100
	v_add_f32_e32 v101, 1.0, v101
	v_rcp_f32_e32 v100, v100
	v_rcp_f32_e32 v101, v101
	v_mul_f32_e32 v91, v96, v91
	v_mul_f32_e32 v96, v92, v99
	v_mul_f32_e32 v92, v97, v100
	v_mul_f32_e32 v93, v93, v101
	v_cvt_pk_bf16_f32 v90, v94, v90
	v_mul_f32_e32 v94, 0xbfb8aa3b, v86
	v_cvt_pk_bf16_f32 v91, v91, v92
	v_cvt_pk_bf16_f32 v92, v98, v95
	v_cvt_pk_bf16_f32 v93, v96, v93
	v_exp_f32_e32 v96, v94
	v_lshl_add_u64 v[94:95], v[122:123], 0, s[2:3]
	global_store_dwordx4 v[94:95], v[90:93], off offset:-4096
	s_mov_b64 s[2:3], 0x30000
	s_bfe_u32 s4, s24, 0x20005
	v_mul_f32_e32 v91, 0xbfb8aa3b, v82
	v_mul_f32_e32 v92, 0xbfb8aa3b, v87
	v_exp_f32_e32 v91, v91
	v_exp_f32_e32 v92, v92
	v_add_f32_e32 v90, 1.0, v96
	v_mul_f32_e32 v93, 0xbfb8aa3b, v83
	v_add_f32_e32 v91, 1.0, v91
	v_add_f32_e32 v92, 1.0, v92
	v_rcp_f32_e32 v90, v90
	v_rcp_f32_e32 v91, v91
	v_rcp_f32_e32 v92, v92
	v_exp_f32_e32 v93, v93
	v_mul_f32_e32 v86, v86, v90
	v_mul_f32_e32 v90, v82, v91
	v_mul_f32_e32 v82, v87, v92
	v_add_f32_e32 v87, 1.0, v93
	v_mul_f32_e32 v91, 0xbfb8aa3b, v88
	v_mul_f32_e32 v92, 0xbfb8aa3b, v84
	v_rcp_f32_e32 v87, v87
	v_exp_f32_e32 v91, v91
	v_exp_f32_e32 v92, v92
	v_mul_f32_e32 v93, 0xbfb8aa3b, v85
	v_mul_f32_e32 v87, v83, v87
	v_add_f32_e32 v83, 1.0, v91
	v_add_f32_e32 v91, 1.0, v92
	v_mul_f32_e32 v92, 0xbfb8aa3b, v89
	v_exp_f32_e32 v92, v92
	v_exp_f32_e32 v93, v93
	v_rcp_f32_e32 v83, v83
	v_rcp_f32_e32 v91, v91
	v_add_f32_e32 v92, 1.0, v92
	v_rcp_f32_e32 v92, v92
	v_add_f32_e32 v93, 1.0, v93
	v_rcp_f32_e32 v93, v93
	v_mul_f32_e32 v83, v88, v83
	v_mul_f32_e32 v88, v84, v91
	v_mul_f32_e32 v84, v89, v92
	v_mul_f32_e32 v85, v85, v93
	v_cvt_pk_bf16_f32 v83, v83, v84
	v_mul_f32_e32 v84, 0xbfb8aa3b, v78
	v_cvt_pk_bf16_f32 v82, v86, v82
	v_exp_f32_e32 v86, v84
	v_cvt_pk_bf16_f32 v84, v90, v87
	v_cvt_pk_bf16_f32 v85, v88, v85
	global_store_dwordx4 v[94:95], v[82:85], off offset:-3840
	v_readlane_b32 s56, v254, 18
	s_lshl_b32 s9, 2, s4
	v_mul_f32_e32 v83, 0xbfb8aa3b, v74
	v_mul_f32_e32 v84, 0xbfb8aa3b, v79
	v_exp_f32_e32 v83, v83
	v_exp_f32_e32 v84, v84
	v_add_f32_e32 v82, 1.0, v86
	v_mul_f32_e32 v85, 0xbfb8aa3b, v75
	v_add_f32_e32 v83, 1.0, v83
	v_add_f32_e32 v84, 1.0, v84
	v_rcp_f32_e32 v82, v82
	v_rcp_f32_e32 v83, v83
	v_rcp_f32_e32 v84, v84
	v_exp_f32_e32 v85, v85
	v_mul_f32_e32 v78, v78, v82
	v_mul_f32_e32 v82, v74, v83
	v_mul_f32_e32 v74, v79, v84
	v_add_f32_e32 v79, 1.0, v85
	v_mul_f32_e32 v83, 0xbfb8aa3b, v80
	v_mul_f32_e32 v84, 0xbfb8aa3b, v76
	v_rcp_f32_e32 v79, v79
	v_exp_f32_e32 v83, v83
	v_exp_f32_e32 v84, v84
	v_mul_f32_e32 v85, 0xbfb8aa3b, v77
	v_mul_f32_e32 v79, v75, v79
	v_add_f32_e32 v75, 1.0, v83
	v_add_f32_e32 v83, 1.0, v84
	v_mul_f32_e32 v84, 0xbfb8aa3b, v81
	v_exp_f32_e32 v84, v84
	v_exp_f32_e32 v85, v85
	v_rcp_f32_e32 v75, v75
	v_rcp_f32_e32 v83, v83
	v_add_f32_e32 v84, 1.0, v84
	v_add_f32_e32 v85, 1.0, v85
	v_rcp_f32_e32 v84, v84
	v_rcp_f32_e32 v85, v85
	v_mul_f32_e32 v75, v80, v75
	v_mul_f32_e32 v80, v76, v83
	v_mul_f32_e32 v76, v81, v84
	v_mul_f32_e32 v77, v77, v85
	v_cvt_pk_bf16_f32 v74, v78, v74
	v_mul_f32_e32 v78, 0xbfb8aa3b, v70
	v_cvt_pk_bf16_f32 v75, v75, v76
	v_cvt_pk_bf16_f32 v76, v82, v79
	v_cvt_pk_bf16_f32 v77, v80, v77
	v_exp_f32_e32 v80, v78
	v_lshl_add_u64 v[78:79], v[122:123], 0, s[2:3]
	global_store_dwordx4 v[78:79], v[74:77], off offset:-4096
	s_mov_b64 s[2:3], 0x80000
	s_lshl_b32 s5, s4, 8
	v_mul_f32_e32 v75, 0xbfb8aa3b, v66
	v_mul_f32_e32 v76, 0xbfb8aa3b, v71
	v_exp_f32_e32 v75, v75
	v_exp_f32_e32 v76, v76
	v_add_f32_e32 v74, 1.0, v80
	v_mul_f32_e32 v77, 0xbfb8aa3b, v67
	v_add_f32_e32 v75, 1.0, v75
	v_add_f32_e32 v76, 1.0, v76
	v_rcp_f32_e32 v74, v74
	v_rcp_f32_e32 v75, v75
	v_rcp_f32_e32 v76, v76
	v_exp_f32_e32 v77, v77
	v_mul_f32_e32 v70, v70, v74
	v_mul_f32_e32 v74, v66, v75
	v_mul_f32_e32 v66, v71, v76
	v_add_f32_e32 v71, 1.0, v77
	v_mul_f32_e32 v75, 0xbfb8aa3b, v72
	v_mul_f32_e32 v76, 0xbfb8aa3b, v68
	v_rcp_f32_e32 v71, v71
	v_exp_f32_e32 v75, v75
	v_exp_f32_e32 v76, v76
	v_mul_f32_e32 v77, 0xbfb8aa3b, v69
; __device__ __forceinline__ u32x4 pack8(const f32x4 v0, const f32x4 v1) { u32x4 w; w.x = pk_f16(v0[0], v0[1]); w.y = pk_f16(v0[2], v0[3]); w.z = pk_f16(v1[0], v1[1]); w.w = pk_f16(v1[2], v1[3]); return w; }
; __device__ __forceinline__ float fast_sigmoid(float v) { return __builtin_amdgcn_rcpf(1.f + __expf(-v)); }
; __device__ __forceinline__ float silu_f(float v) { return v * fast_sigmoid(v); }
;     __device__ __forceinline__ void operator()(AccRef acc, const Unit& u, int wr, int wc, int fr, int fq) const {
;     ...
;                     else {
; #pragma unroll
;                         for (int j = 0; j < 4; ++j) { v0[j] = silu_f(v0[j]); v1[j] = silu_f(v1[j]); }
;                         *(u32x4*)(zs + (size_t)row * D + (col - PW - SW)) = pack8(v0, v1); } } }
	v_mul_f32_e32 v71, v67, v71
	v_add_f32_e32 v67, 1.0, v75
	v_add_f32_e32 v75, 1.0, v76
	v_mul_f32_e32 v76, 0xbfb8aa3b, v73
	v_exp_f32_e32 v76, v76
	v_exp_f32_e32 v77, v77
	v_rcp_f32_e32 v67, v67
	v_rcp_f32_e32 v75, v75
	v_add_f32_e32 v76, 1.0, v76
	v_rcp_f32_e32 v76, v76
	v_add_f32_e32 v77, 1.0, v77
	v_rcp_f32_e32 v77, v77
	v_mul_f32_e32 v67, v72, v67
	v_mul_f32_e32 v72, v68, v75
	v_mul_f32_e32 v68, v73, v76
	v_mul_f32_e32 v69, v69, v77
	v_cvt_pk_bf16_f32 v67, v67, v68
	v_mul_f32_e32 v68, 0xbfb8aa3b, v62
	v_cvt_pk_bf16_f32 v66, v70, v66
	v_exp_f32_e32 v70, v68
	v_cvt_pk_bf16_f32 v68, v74, v71
	v_cvt_pk_bf16_f32 v69, v72, v69
	global_store_dwordx4 v[78:79], v[66:69], off offset:-3840
	v_readlane_b32 s58, v254, 20
	v_readlane_b32 s59, v254, 21
	v_mul_f32_e32 v67, 0xbfb8aa3b, v58
	v_mul_f32_e32 v68, 0xbfb8aa3b, v63
	v_exp_f32_e32 v67, v67
	v_exp_f32_e32 v68, v68
	v_add_f32_e32 v66, 1.0, v70
	v_mul_f32_e32 v69, 0xbfb8aa3b, v59
	v_add_f32_e32 v67, 1.0, v67
	v_add_f32_e32 v68, 1.0, v68
	v_rcp_f32_e32 v66, v66
	v_rcp_f32_e32 v67, v67
	v_rcp_f32_e32 v68, v68
	v_exp_f32_e32 v69, v69
	v_mul_f32_e32 v62, v62, v66
	v_mul_f32_e32 v66, v58, v67
	v_mul_f32_e32 v58, v63, v68
	v_add_f32_e32 v63, 1.0, v69
	v_mul_f32_e32 v67, 0xbfb8aa3b, v64
	v_mul_f32_e32 v68, 0xbfb8aa3b, v60
	v_rcp_f32_e32 v63, v63
	v_exp_f32_e32 v67, v67
	v_exp_f32_e32 v68, v68
	v_mul_f32_e32 v69, 0xbfb8aa3b, v61
	v_mul_f32_e32 v63, v59, v63
	v_add_f32_e32 v59, 1.0, v67
	v_add_f32_e32 v67, 1.0, v68
	v_mul_f32_e32 v68, 0xbfb8aa3b, v65
	v_exp_f32_e32 v68, v68
	v_exp_f32_e32 v69, v69
	v_rcp_f32_e32 v59, v59
	v_rcp_f32_e32 v67, v67
	v_add_f32_e32 v68, 1.0, v68
	v_add_f32_e32 v69, 1.0, v69
	v_rcp_f32_e32 v68, v68
	v_rcp_f32_e32 v69, v69
	v_mul_f32_e32 v59, v64, v59
	v_mul_f32_e32 v64, v60, v67
	v_mul_f32_e32 v60, v65, v68
	v_mul_f32_e32 v61, v61, v69
	v_cvt_pk_bf16_f32 v58, v62, v58
	v_mul_f32_e32 v62, 0xbfb8aa3b, v54
	v_cvt_pk_bf16_f32 v59, v59, v60
	v_cvt_pk_bf16_f32 v60, v66, v63
	v_cvt_pk_bf16_f32 v61, v64, v61
	v_exp_f32_e32 v64, v62
	v_lshl_add_u64 v[62:63], v[122:123], 0, s[2:3]
	global_store_dwordx4 v[62:63], v[58:61], off offset:-4096
	s_mov_b64 s[2:3], 0x90000
	s_lshl_b32 s8, s28, 1
	v_mul_f32_e32 v59, 0xbfb8aa3b, v50
	v_mul_f32_e32 v60, 0xbfb8aa3b, v55
	v_exp_f32_e32 v59, v59
	v_exp_f32_e32 v60, v60
	v_add_f32_e32 v58, 1.0, v64
	v_mul_f32_e32 v61, 0xbfb8aa3b, v51
	v_add_f32_e32 v59, 1.0, v59
	v_add_f32_e32 v60, 1.0, v60
	v_rcp_f32_e32 v58, v58
	v_rcp_f32_e32 v59, v59
	v_rcp_f32_e32 v60, v60
	v_exp_f32_e32 v61, v61
	v_mul_f32_e32 v54, v54, v58
	v_mul_f32_e32 v58, v50, v59
	v_mul_f32_e32 v50, v55, v60
	v_add_f32_e32 v55, 1.0, v61
	v_mul_f32_e32 v59, 0xbfb8aa3b, v56
	v_mul_f32_e32 v60, 0xbfb8aa3b, v52
	v_rcp_f32_e32 v55, v55
	v_exp_f32_e32 v59, v59
	v_exp_f32_e32 v60, v60
	v_mul_f32_e32 v61, 0xbfb8aa3b, v53
	v_mul_f32_e32 v55, v51, v55
	v_add_f32_e32 v51, 1.0, v59
	v_add_f32_e32 v59, 1.0, v60
	v_mul_f32_e32 v60, 0xbfb8aa3b, v57
	v_exp_f32_e32 v60, v60
	v_exp_f32_e32 v61, v61
	v_rcp_f32_e32 v51, v51
	v_rcp_f32_e32 v59, v59
	v_add_f32_e32 v60, 1.0, v60
	v_rcp_f32_e32 v60, v60
	v_add_f32_e32 v61, 1.0, v61
	v_rcp_f32_e32 v61, v61
	v_mul_f32_e32 v51, v56, v51
	v_mul_f32_e32 v56, v52, v59
	v_mul_f32_e32 v52, v57, v60
	v_mul_f32_e32 v53, v53, v61
	v_cvt_pk_bf16_f32 v51, v51, v52
	v_mul_f32_e32 v52, 0xbfb8aa3b, v46
	v_cvt_pk_bf16_f32 v50, v54, v50
	v_exp_f32_e32 v54, v52
	v_cvt_pk_bf16_f32 v52, v58, v55
	v_cvt_pk_bf16_f32 v53, v56, v53
	global_store_dwordx4 v[62:63], v[50:53], off offset:-3840
	s_lshr_b32 s33, s9, 1
	s_lshl_b32 s6, s4, 10
	v_mul_f32_e32 v51, 0xbfb8aa3b, v42
	v_mul_f32_e32 v52, 0xbfb8aa3b, v47
	v_exp_f32_e32 v51, v51
	v_exp_f32_e32 v52, v52
	v_add_f32_e32 v50, 1.0, v54
	v_mul_f32_e32 v53, 0xbfb8aa3b, v43
	v_add_f32_e32 v51, 1.0, v51
	v_add_f32_e32 v52, 1.0, v52
	v_rcp_f32_e32 v50, v50
	v_rcp_f32_e32 v51, v51
	v_rcp_f32_e32 v52, v52
	v_exp_f32_e32 v53, v53
	v_mul_f32_e32 v46, v46, v50
	v_mul_f32_e32 v50, v42, v51
	v_mul_f32_e32 v42, v47, v52
	v_add_f32_e32 v47, 1.0, v53
	v_mul_f32_e32 v51, 0xbfb8aa3b, v48
	v_mul_f32_e32 v52, 0xbfb8aa3b, v44
	v_rcp_f32_e32 v47, v47
	v_exp_f32_e32 v51, v51
	v_exp_f32_e32 v52, v52
	v_mul_f32_e32 v53, 0xbfb8aa3b, v45
	v_mul_f32_e32 v47, v43, v47
	v_add_f32_e32 v43, 1.0, v51
	v_add_f32_e32 v51, 1.0, v52
	v_mul_f32_e32 v52, 0xbfb8aa3b, v49
	v_exp_f32_e32 v52, v52
	v_exp_f32_e32 v53, v53
	v_rcp_f32_e32 v43, v43
	v_rcp_f32_e32 v51, v51
	v_add_f32_e32 v52, 1.0, v52
	v_add_f32_e32 v53, 1.0, v53
	v_rcp_f32_e32 v52, v52
	v_rcp_f32_e32 v53, v53
	v_mul_f32_e32 v43, v48, v43
	v_mul_f32_e32 v48, v44, v51
	v_mul_f32_e32 v44, v49, v52
	v_mul_f32_e32 v45, v45, v53
	v_cvt_pk_bf16_f32 v42, v46, v42
	v_mul_f32_e32 v46, 0xbfb8aa3b, v38
	v_cvt_pk_bf16_f32 v43, v43, v44
	v_cvt_pk_bf16_f32 v44, v50, v47
	v_cvt_pk_bf16_f32 v45, v48, v45
	v_exp_f32_e32 v48, v46
	v_lshl_add_u64 v[46:47], v[122:123], 0, s[2:3]
	global_store_dwordx4 v[46:47], v[42:45], off offset:-4096
	s_mov_b64 s[2:3], 0xa0000
	s_mov_b64 s[54:55], s[58:59]
	v_mul_f32_e32 v43, 0xbfb8aa3b, v34
	v_mul_f32_e32 v44, 0xbfb8aa3b, v39
	v_exp_f32_e32 v43, v43
	v_exp_f32_e32 v44, v44
	v_add_f32_e32 v42, 1.0, v48
	v_mul_f32_e32 v45, 0xbfb8aa3b, v35
	v_add_f32_e32 v43, 1.0, v43
	v_add_f32_e32 v44, 1.0, v44
	v_rcp_f32_e32 v42, v42
	v_rcp_f32_e32 v43, v43
	v_rcp_f32_e32 v44, v44
	v_exp_f32_e32 v45, v45
	v_mul_f32_e32 v38, v38, v42
	v_mul_f32_e32 v42, v34, v43
	v_mul_f32_e32 v34, v39, v44
	v_add_f32_e32 v39, 1.0, v45
	v_mul_f32_e32 v43, 0xbfb8aa3b, v40
	v_mul_f32_e32 v44, 0xbfb8aa3b, v36
	v_rcp_f32_e32 v39, v39
	v_exp_f32_e32 v43, v43
	v_exp_f32_e32 v44, v44
	v_mul_f32_e32 v45, 0xbfb8aa3b, v37
	v_mul_f32_e32 v39, v35, v39
; __device__ __forceinline__ float silu_f(float v) { return v * fast_sigmoid(v); }
; __device__ __forceinline__ u32x4 pack8(const f32x4 v0, const f32x4 v1) { u32x4 w; w.x = pk_f16(v0[0], v0[1]); w.y = pk_f16(v0[2], v0[3]); w.z = pk_f16(v1[0], v1[1]); w.w = pk_f16(v1[2], v1[3]); return w; }
; __device__ __forceinline__ unsigned xb_ld(unsigned* p)              { return __hip_atomic_load(p, __ATOMIC_RELAXED, __HIP_MEMORY_SCOPE_AGENT); }
; __device__ __forceinline__ unsigned xb_add(unsigned* p, unsigned v) { return __hip_atomic_fetch_add(p, v, __ATOMIC_RELAXED, __HIP_MEMORY_SCOPE_AGENT); }
;     __device__ __forceinline__ void operator()(AccRef acc, const Unit& u, int wr, int wc, int fr, int fq) const {
;     ...
;                     else {
; #pragma unroll
;                         for (int j = 0; j < 4; ++j) { v0[j] = silu_f(v0[j]); v1[j] = silu_f(v1[j]); }
;                         *(u32x4*)(zs + (size_t)row * D + (col - PW - SW)) = pack8(v0, v1); } } }
; __device__ __forceinline__ void xcd_barrier(const XcdBarrier& b) {
;     asm volatile("s_waitcnt vmcnt(0)" ::: "memory");
;     __syncthreads();
;     if (threadIdx.x == 0) {
;         unsigned* bar = b.bar;
;         __builtin_amdgcn_s_waitcnt(0);
;         unsigned nloc = b.st[0], nx = b.st[1];
;         if (nloc == 0u) { xcd_barrier_complete(bar, b.x, nloc, nx); b.st[0] = nloc; b.st[1] = nx; }
;         const unsigned old = xb_add(&bar[XB_XSUB(b.x)], 1u);
;         const unsigned gen = old / nloc;
;         if (old + 1u == (gen + 1u) * nloc) {
;             __builtin_amdgcn_fence(__ATOMIC_RELEASE, "agent");
;             asm volatile("s_waitcnt vmcnt(0)" ::: "memory");
;             const unsigned og = xb_add(&bar[XB_TOP], 1u);
;             const unsigned tg = og / nx;
;             if (og + 1u == (tg + 1u) * nx) xb_add(&bar[XB_TOPGEN], 1u);
;             else XB_SPIN(xb_ld(&bar[XB_TOPGEN]) == tg, bar);
;             __builtin_amdgcn_fence(__ATOMIC_ACQUIRE, "agent");
;             xb_add(&bar[XB_XGEN(b.x)], 1u);
;             asm volatile("s_waitcnt vmcnt(0)" ::: "memory");
;         } else {
;             XB_SPIN(xb_ld(&bar[XB_XGEN(b.x)]) == gen, bar);
;             __builtin_amdgcn_fence(__ATOMIC_ACQUIRE, "agent");
;             asm volatile("s_waitcnt vmcnt(0)" ::: "memory");
;         }
;     }
;     __syncthreads();
	v_add_f32_e32 v35, 1.0, v43
	v_add_f32_e32 v43, 1.0, v44
	v_mul_f32_e32 v44, 0xbfb8aa3b, v41
	v_exp_f32_e32 v44, v44
	v_exp_f32_e32 v45, v45
	v_rcp_f32_e32 v35, v35
	v_rcp_f32_e32 v43, v43
	v_add_f32_e32 v44, 1.0, v44
	v_rcp_f32_e32 v44, v44
	v_add_f32_e32 v45, 1.0, v45
	v_rcp_f32_e32 v45, v45
	v_mul_f32_e32 v35, v40, v35
	v_mul_f32_e32 v40, v36, v43
	v_mul_f32_e32 v36, v41, v44
	v_mul_f32_e32 v37, v37, v45
	v_cvt_pk_bf16_f32 v35, v35, v36
	v_mul_f32_e32 v36, 0xbfb8aa3b, v30
	v_cvt_pk_bf16_f32 v34, v38, v34
	v_exp_f32_e32 v38, v36
	v_cvt_pk_bf16_f32 v36, v42, v39
	v_cvt_pk_bf16_f32 v37, v40, v37
	global_store_dwordx4 v[46:47], v[34:37], off offset:-3840
	v_mov_b32_e32 v171, 0
	v_readlane_b32 s57, v254, 19
	v_mul_f32_e32 v35, 0xbfb8aa3b, v26
	v_mul_f32_e32 v36, 0xbfb8aa3b, v31
	v_exp_f32_e32 v35, v35
	v_exp_f32_e32 v36, v36
	v_add_f32_e32 v34, 1.0, v38
	v_mul_f32_e32 v37, 0xbfb8aa3b, v27
	v_add_f32_e32 v35, 1.0, v35
	v_add_f32_e32 v36, 1.0, v36
	v_rcp_f32_e32 v34, v34
	v_rcp_f32_e32 v35, v35
	v_rcp_f32_e32 v36, v36
	v_exp_f32_e32 v37, v37
	v_mul_f32_e32 v30, v30, v34
	v_mul_f32_e32 v34, v26, v35
	v_mul_f32_e32 v26, v31, v36
	v_add_f32_e32 v31, 1.0, v37
	v_mul_f32_e32 v35, 0xbfb8aa3b, v32
	v_mul_f32_e32 v36, 0xbfb8aa3b, v28
	v_rcp_f32_e32 v31, v31
	v_exp_f32_e32 v35, v35
	v_exp_f32_e32 v36, v36
	v_mul_f32_e32 v37, 0xbfb8aa3b, v29
	v_mul_f32_e32 v31, v27, v31
	v_add_f32_e32 v27, 1.0, v35
	v_add_f32_e32 v35, 1.0, v36
	v_mul_f32_e32 v36, 0xbfb8aa3b, v33
	v_exp_f32_e32 v36, v36
	v_exp_f32_e32 v37, v37
	v_rcp_f32_e32 v27, v27
	v_rcp_f32_e32 v35, v35
	v_add_f32_e32 v36, 1.0, v36
	v_add_f32_e32 v37, 1.0, v37
	v_rcp_f32_e32 v36, v36
	v_rcp_f32_e32 v37, v37
	v_mul_f32_e32 v27, v32, v27
	v_mul_f32_e32 v32, v28, v35
	v_mul_f32_e32 v28, v33, v36
	v_mul_f32_e32 v29, v29, v37
	v_cvt_pk_bf16_f32 v26, v30, v26
	v_mul_f32_e32 v30, 0xbfb8aa3b, v22
	v_cvt_pk_bf16_f32 v27, v27, v28
	v_cvt_pk_bf16_f32 v28, v34, v31
	v_cvt_pk_bf16_f32 v29, v32, v29
	v_exp_f32_e32 v32, v30
	v_lshl_add_u64 v[30:31], v[122:123], 0, s[2:3]
	global_store_dwordx4 v[30:31], v[26:29], off offset:-4096
	s_mov_b64 s[2:3], 0xb0000
	v_readlane_b32 s60, v254, 22
	v_mul_f32_e32 v27, 0xbfb8aa3b, v18
	v_mul_f32_e32 v28, 0xbfb8aa3b, v23
	v_exp_f32_e32 v27, v27
	v_exp_f32_e32 v28, v28
	v_add_f32_e32 v26, 1.0, v32
	v_mul_f32_e32 v29, 0xbfb8aa3b, v19
	v_add_f32_e32 v27, 1.0, v27
	v_add_f32_e32 v28, 1.0, v28
	v_rcp_f32_e32 v26, v26
	v_rcp_f32_e32 v27, v27
	v_rcp_f32_e32 v28, v28
	v_exp_f32_e32 v29, v29
	v_mul_f32_e32 v22, v22, v26
	v_mul_f32_e32 v26, v18, v27
	v_mul_f32_e32 v18, v23, v28
	v_add_f32_e32 v23, 1.0, v29
	v_mul_f32_e32 v27, 0xbfb8aa3b, v24
	v_mul_f32_e32 v28, 0xbfb8aa3b, v20
	v_rcp_f32_e32 v23, v23
	v_exp_f32_e32 v27, v27
	v_exp_f32_e32 v28, v28
	v_mul_f32_e32 v29, 0xbfb8aa3b, v21
	v_mul_f32_e32 v23, v19, v23
	v_add_f32_e32 v19, 1.0, v27
	v_add_f32_e32 v27, 1.0, v28
	v_mul_f32_e32 v28, 0xbfb8aa3b, v25
	v_exp_f32_e32 v28, v28
	v_exp_f32_e32 v29, v29
	v_rcp_f32_e32 v19, v19
	v_rcp_f32_e32 v27, v27
	v_add_f32_e32 v28, 1.0, v28
	v_rcp_f32_e32 v28, v28
	v_add_f32_e32 v29, 1.0, v29
	v_rcp_f32_e32 v29, v29
	v_mul_f32_e32 v19, v24, v19
	v_mul_f32_e32 v24, v20, v27
	v_mul_f32_e32 v20, v25, v28
	v_mul_f32_e32 v21, v21, v29
	v_cvt_pk_bf16_f32 v19, v19, v20
	v_mul_f32_e32 v20, 0xbfb8aa3b, v14
	v_cvt_pk_bf16_f32 v18, v22, v18
	v_exp_f32_e32 v22, v20
	v_cvt_pk_bf16_f32 v20, v26, v23
	v_cvt_pk_bf16_f32 v21, v24, v21
	global_store_dwordx4 v[30:31], v[18:21], off offset:-3840
	v_readlane_b32 s61, v254, 23
	v_readlane_b32 s62, v254, 24
	v_mul_f32_e32 v19, 0xbfb8aa3b, v10
	v_mul_f32_e32 v20, 0xbfb8aa3b, v15
	v_exp_f32_e32 v19, v19
	v_exp_f32_e32 v20, v20
	v_add_f32_e32 v18, 1.0, v22
	v_mul_f32_e32 v21, 0xbfb8aa3b, v11
	v_add_f32_e32 v19, 1.0, v19
	v_add_f32_e32 v20, 1.0, v20
	v_rcp_f32_e32 v18, v18
	v_rcp_f32_e32 v19, v19
	v_rcp_f32_e32 v20, v20
	v_exp_f32_e32 v21, v21
	v_mul_f32_e32 v14, v14, v18
	v_mul_f32_e32 v18, v10, v19
	v_mul_f32_e32 v10, v15, v20
	v_add_f32_e32 v15, 1.0, v21
	v_mul_f32_e32 v19, 0xbfb8aa3b, v16
	v_mul_f32_e32 v20, 0xbfb8aa3b, v12
	v_rcp_f32_e32 v15, v15
	v_exp_f32_e32 v19, v19
	v_exp_f32_e32 v20, v20
	v_mul_f32_e32 v21, 0xbfb8aa3b, v13
	v_mul_f32_e32 v15, v11, v15
	v_add_f32_e32 v11, 1.0, v19
	v_add_f32_e32 v19, 1.0, v20
	v_mul_f32_e32 v20, 0xbfb8aa3b, v17
	v_exp_f32_e32 v20, v20
	v_exp_f32_e32 v21, v21
	v_rcp_f32_e32 v11, v11
	v_rcp_f32_e32 v19, v19
	v_add_f32_e32 v20, 1.0, v20
	v_add_f32_e32 v21, 1.0, v21
	v_rcp_f32_e32 v20, v20
	v_rcp_f32_e32 v21, v21
	v_mul_f32_e32 v11, v16, v11
	v_mul_f32_e32 v16, v12, v19
	v_mul_f32_e32 v12, v17, v20
	v_mul_f32_e32 v13, v13, v21
	v_cvt_pk_bf16_f32 v10, v14, v10
	v_mul_f32_e32 v14, 0xbfb8aa3b, v6
	v_cvt_pk_bf16_f32 v11, v11, v12
	v_cvt_pk_bf16_f32 v12, v18, v15
	v_cvt_pk_bf16_f32 v13, v16, v13
	v_exp_f32_e32 v16, v14
	v_lshl_add_u64 v[14:15], v[122:123], 0, s[2:3]
	global_store_dwordx4 v[14:15], v[10:13], off offset:-4096
	s_or_b32 s2, s35, s24
	s_ashr_i32 s2, s2, 7
	v_mul_f32_e32 v11, 0xbfb8aa3b, v2
	v_mul_f32_e32 v12, 0xbfb8aa3b, v7
	v_exp_f32_e32 v11, v11
	v_exp_f32_e32 v12, v12
	v_add_f32_e32 v10, 1.0, v16
	v_mul_f32_e32 v13, 0xbfb8aa3b, v3
	v_add_f32_e32 v11, 1.0, v11
	v_add_f32_e32 v12, 1.0, v12
	v_rcp_f32_e32 v10, v10
	v_rcp_f32_e32 v11, v11
	v_rcp_f32_e32 v12, v12
	v_exp_f32_e32 v13, v13
	v_mul_f32_e32 v6, v6, v10
	v_mul_f32_e32 v10, v2, v11
	v_mul_f32_e32 v2, v7, v12
	v_add_f32_e32 v7, 1.0, v13
	v_mul_f32_e32 v11, 0xbfb8aa3b, v8
	v_mul_f32_e32 v12, 0xbfb8aa3b, v4
	v_rcp_f32_e32 v7, v7
	v_exp_f32_e32 v11, v11
	v_exp_f32_e32 v12, v12
	v_mul_f32_e32 v13, 0xbfb8aa3b, v5
	v_mul_f32_e32 v7, v3, v7
	v_add_f32_e32 v3, 1.0, v11
	v_add_f32_e32 v11, 1.0, v12
	v_mul_f32_e32 v12, 0xbfb8aa3b, v9
	v_exp_f32_e32 v12, v12
	v_exp_f32_e32 v13, v13
	v_rcp_f32_e32 v3, v3
	v_rcp_f32_e32 v11, v11
	v_add_f32_e32 v12, 1.0, v12
	v_add_f32_e32 v13, 1.0, v13
	v_rcp_f32_e32 v12, v12
	v_rcp_f32_e32 v13, v13
	v_mul_f32_e32 v3, v8, v3
	v_mul_f32_e32 v8, v4, v11
	v_mul_f32_e32 v4, v9, v12
	v_mul_f32_e32 v5, v5, v13
	v_cvt_pk_bf16_f32 v2, v6, v2
	v_cvt_pk_bf16_f32 v3, v3, v4
	v_cvt_pk_bf16_f32 v4, v10, v7
	v_cvt_pk_bf16_f32 v5, v8, v5
	global_store_dwordx4 v[14:15], v[2:5], off offset:-3840
	v_mov_b32_e32 v16, v0
	s_ashr_i32 s3, s2, 31
	s_waitcnt vmcnt(0)
	s_barrier
	s_mov_b64 s[98:99], exec
	s_and_b64 exec, exec, s[82:83]
	s_cbranch_execz .Lp3_wp_done
	v_mov_b32_e32 v2, 0x3500
	s_mov_b32 s101, 0
.Lp3_wp:
	global_load_dword v3, v2, s[50:51] sc1
	s_add_u32 s101, s101, 1
	s_waitcnt vmcnt(0)
	v_readfirstlane_b32 vcc_lo, v3
	s_cmp_lg_u32 vcc_lo, 2
	s_cbranch_scc1 .Lp3_wp_polled
	s_cmp_gt_u32 s101, 0x4000
	s_cbranch_scc1 .Lp3_wp_polled
	s_sleep 1
	s_branch .Lp3_wp

; #define LAS __attribute__((address_space(3)))
; __device__ __forceinline__ void pm_item(LAS float* Vs0, int item, const f16* up, const f16* zs, const float* pscale, f16* branch) {
;     int tid = threadIdx.x; asm volatile("" : "+v"(tid));
;     const int b = item >> 7, g = (item >> 5) & 3, band = item & 31, r0 = band * 4;
;     const int w = 2 << g, lo_off = w >> 1, hi_off = w - lo_off;
;     const int o = tid & 31, cs = tid >> 5;
;     const f16* ub = up + (size_t)b * SEQ * PW + g * 256 + o * 8 + (size_t)(4 * cs) * PW;
;     const size_t zoff = (size_t)b * SEQ * D + g * 256 + o * 8 + (size_t)(4 * cs) * D;
;     const f32x4 sc0 = *(const f32x4*)(pscale + g * 256 + o * 8), sc1 = *(const f32x4*)(pscale + g * 256 + o * 8 + 4);
;     float rs[4][8];
; #pragma unroll
;     for (int q = 0; q < 4; ++q)
; #pragma unroll
;         for (int e = 0; e < 8; ++e) rs[q][e] = 0.f;
;     u32x4 cen[2][4], zz[2][4], hi[2][4], lo[2][4];
; #pragma unroll
;     for (int q = 0; q < 4; ++q) { cen[0][q] = *(const u32x4*)(ub + (size_t)(r0 * GW + q) * PW); zz[0][q] = *(const u32x4*)(zs + zoff + (size_t)(r0 * GW + q) * D); }
.Lp3_wp_done:
	s_mov_b64 exec, s[98:99]
	s_barrier
	s_lshl_b64 s[2:3], s[2:3], 24
	v_ashrrev_i32_e32 v222, 3, v16
	v_lshlrev_b32_e32 v2, 3, v16
	v_and_b32_e32 v206, -4, v222
	s_or_b32 s5, s2, s5
	v_and_b32_e32 v221, 0xf8, v2
	v_ashrrev_i32_e32 v207, 31, v206
	s_add_u32 s6, s54, s6
	v_lshlrev_b64 v[10:11], 11, v[206:207]
	s_addc_u32 s7, s55, 0
	v_lshlrev_b32_e32 v207, 2, v221
	s_and_b32 s45, s8, 0x7c
	global_load_dwordx4 v[2:5], v207, s[6:7] offset:16
	global_load_dwordx4 v[6:9], v207, s[6:7]
	s_add_u32 s6, s0, s2
	s_addc_u32 s7, s1, s3
	s_lshl_b32 s4, s4, 9
	s_add_u32 s6, s6, s4
	s_addc_u32 s7, s7, 0
	v_lshlrev_b32_e32 v170, 1, v221
	v_or_b32_e32 v12, s5, v221
	v_mov_b32_e32 v13, s3
	v_lshl_add_u64 v[14:15], s[6:7], 0, v[170:171]
	s_lshl_b32 s55, s45, 6
	s_mov_b32 s5, 0
	v_lshl_add_u64 v[202:203], v[14:15], 0, v[10:11]
	v_lshl_add_u64 v[208:209], v[12:13], 0, v[10:11]
	s_lshl_b32 s4, s45, 17
	s_or_b32 s8, s55, 1
	v_lshl_add_u64 v[204:205], v[208:209], 1, s[92:93]
	v_lshl_add_u64 v[12:13], v[202:203], 0, s[4:5]
	s_lshl_b32 s4, s45, 18
	s_lshl_b32 s6, s8, 11
	s_mov_b32 s7, s5
	v_lshl_add_u64 v[14:15], v[204:205], 0, s[4:5]
	global_load_dwordx4 v[78:81], v[12:13], off
	global_load_dwordx4 v[86:89], v[14:15], off
	v_lshl_add_u64 v[12:13], v[202:203], 0, s[6:7]
	s_lshl_b32 s6, s8, 12
	s_or_b32 s8, s55, 2
	v_lshl_add_u64 v[14:15], v[204:205], 0, s[6:7]
	s_lshl_b32 s6, s8, 11
	global_load_dwordx4 v[58:61], v[12:13], off
	global_load_dwordx4 v[66:69], v[14:15], off
	v_lshl_add_u64 v[12:13], v[202:203], 0, s[6:7]
	s_lshl_b32 s6, s8, 12
	s_or_b32 s8, s55, 3
	v_lshl_add_u64 v[14:15], v[204:205], 0, s[6:7]
	s_lshl_b32 s6, s8, 11
	global_load_dwordx4 v[50:53], v[12:13], off
	global_load_dwordx4 v[54:57], v[14:15], off
	v_lshl_add_u64 v[12:13], v[202:203], 0, s[6:7]
	s_lshl_b32 s6, s8, 12
	v_lshl_add_u64 v[14:15], v[204:205], 0, s[6:7]
	global_load_dwordx4 v[42:45], v[12:13], off
	global_load_dwordx4 v[46:49], v[14:15], off
	v_readlane_b32 s63, v254, 25
	v_readlane_b32 s64, v254, 26
	v_readlane_b32 s65, v254, 27
	s_mov_b64 s[56:57], s[60:61]
	s_sub_i32 s44, s9, s33
	s_sub_i32 s41, s45, s33
	s_add_i32 s56, s44, s45
	s_max_i32 s5, s41, 0
	s_min_i32 s40, s56, 0x80
	s_mov_b32 s81, s28
	s_cmp_le_i32 s40, s5
	v_and_b32_e32 v220, 31, v16
	v_readlane_b32 s66, v254, 28
	v_readlane_b32 s67, v254, 29
	v_readlane_b32 s68, v254, 30
	v_readlane_b32 s69, v254, 31
	v_readlane_b32 s70, v254, 32
	v_readlane_b32 s71, v254, 33
	s_mov_b64 s[58:59], s[62:63]
	s_mov_b64 s[60:61], s[64:65]
	s_cbranch_scc1 .LBB0_530
	s_lshl_b32 s6, s5, 17
	s_add_u32 s2, s2, s6
	s_addc_u32 s3, s3, 0
	s_lshl_b32 s6, s24, 4
	s_and_b32 s6, s6, 0x600
	s_add_u32 s2, s6, s2
	s_addc_u32 s3, 0, s3
	v_lshl_add_u64 v[10:11], s[2:3], 0, v[10:11]
	v_lshlrev_b32_e32 v170, 4, v220
	v_lshl_add_u64 v[10:11], v[10:11], 0, v[170:171]
	v_lshl_add_u64 v[10:11], s[50:51], 0, v[10:11]
	s_mov_b64 s[2:3], 0xa3e1800
	v_mov_b32_e32 v170, v171
	v_lshl_add_u64 v[210:211], v[10:11], 0, s[2:3]
	s_mov_b32 s54, 0xfff1f000
	s_mov_b64 s[2:3], 0x100000
	s_mov_b32 s57, s5
	v_mov_b64_e32 v[200:201], v[170:171]
	v_mov_b64_e32 v[196:197], v[170:171]
	v_mov_b64_e32 v[198:199], v[170:171]
	v_mov_b64_e32 v[192:193], v[170:171]
	v_mov_b64_e32 v[194:195], v[170:171]
	v_mov_b64_e32 v[188:189], v[170:171]
	v_mov_b64_e32 v[190:191], v[170:171]
	v_mov_b64_e32 v[184:185], v[170:171]
	v_mov_b64_e32 v[186:187], v[170:171]
	v_mov_b64_e32 v[180:181], v[170:171]
	v_mov_b64_e32 v[182:183], v[170:171]
	v_mov_b64_e32 v[176:177], v[170:171]
	v_mov_b64_e32 v[178:179], v[170:171]
	v_mov_b64_e32 v[172:173], v[170:171]
	v_mov_b64_e32 v[174:175], v[170:171]
	s_branch .LBB0_501

; __device__ __forceinline__ unsigned xb_ld(unsigned* p)              { return __hip_atomic_load(p, __ATOMIC_RELAXED, __HIP_MEMORY_SCOPE_AGENT); }
; __device__ __forceinline__ unsigned xb_add(unsigned* p, unsigned v) { return __hip_atomic_fetch_add(p, v, __ATOMIC_RELAXED, __HIP_MEMORY_SCOPE_AGENT); }
; #define XB_SPIN(cond, bar) do { unsigned _sp = 0; while (cond) { __builtin_amdgcn_s_sleep(1); \
;     if ((++_sp & 255u) == 0u) { if (xb_ld(&(bar)[XB_TMO])) break; if (_sp > XB_SPIN_CAP) { atomicAdd(&(bar)[XB_TMO], 1u); break; } } } } while (0)
; __device__ __forceinline__ void xcd_barrier(const XcdBarrier& b) {
;     asm volatile("s_waitcnt vmcnt(0)" ::: "memory");
;     __syncthreads();
;     if (threadIdx.x == 0) {
;         unsigned* bar = b.bar;
;         __builtin_amdgcn_s_waitcnt(0);
;         unsigned nloc = b.st[0], nx = b.st[1];
;         if (nloc == 0u) { xcd_barrier_complete(bar, b.x, nloc, nx); b.st[0] = nloc; b.st[1] = nx; }
;         const unsigned old = xb_add(&bar[XB_XSUB(b.x)], 1u);
;         const unsigned gen = old / nloc;
;         if (old + 1u == (gen + 1u) * nloc) {
;             __builtin_amdgcn_fence(__ATOMIC_RELEASE, "agent");
;             asm volatile("s_waitcnt vmcnt(0)" ::: "memory");
;             const unsigned og = xb_add(&bar[XB_TOP], 1u);
;             const unsigned tg = og / nx;
;             if (og + 1u == (tg + 1u) * nx) xb_add(&bar[XB_TOPGEN], 1u);
;             else XB_SPIN(xb_ld(&bar[XB_TOPGEN]) == tg, bar);
;             __builtin_amdgcn_fence(__ATOMIC_ACQUIRE, "agent");
;             xb_add(&bar[XB_XGEN(b.x)], 1u);
;             asm volatile("s_waitcnt vmcnt(0)" ::: "memory");
;         } else {
;             XB_SPIN(xb_ld(&bar[XB_XGEN(b.x)]) == gen, bar);
;             __builtin_amdgcn_fence(__ATOMIC_ACQUIRE, "agent");
;             asm volatile("s_waitcnt vmcnt(0)" ::: "memory");
;         }
;     }
;     __syncthreads();
.LBB0_529:
	s_mov_b64 s[98:99], exec
	s_and_b64 exec, exec, s[82:83]
	s_cbranch_execz .Lp3_wc_done
	v_mov_b32_e32 v2, 0x3500
	s_mov_b32 s101, 0

; __device__ __forceinline__ unsigned xb_ld(unsigned* p)              { return __hip_atomic_load(p, __ATOMIC_RELAXED, __HIP_MEMORY_SCOPE_AGENT); }
; __device__ __forceinline__ unsigned xb_add(unsigned* p, unsigned v) { return __hip_atomic_fetch_add(p, v, __ATOMIC_RELAXED, __HIP_MEMORY_SCOPE_AGENT); }
; #define XB_SPIN(cond, bar) do { unsigned _sp = 0; while (cond) { __builtin_amdgcn_s_sleep(1); \
;     if ((++_sp & 255u) == 0u) { if (xb_ld(&(bar)[XB_TMO])) break; if (_sp > XB_SPIN_CAP) { atomicAdd(&(bar)[XB_TMO], 1u); break; } } } } while (0)
; __device__ __forceinline__ void xcd_barrier(const XcdBarrier& b) {
;     asm volatile("s_waitcnt vmcnt(0)" ::: "memory");
;     __syncthreads();
;     if (threadIdx.x == 0) {
;         unsigned* bar = b.bar;
;         __builtin_amdgcn_s_waitcnt(0);
;         unsigned nloc = b.st[0], nx = b.st[1];
;         if (nloc == 0u) { xcd_barrier_complete(bar, b.x, nloc, nx); b.st[0] = nloc; b.st[1] = nx; }
;         const unsigned old = xb_add(&bar[XB_XSUB(b.x)], 1u);
;         const unsigned gen = old / nloc;
;         if (old + 1u == (gen + 1u) * nloc) {
;             __builtin_amdgcn_fence(__ATOMIC_RELEASE, "agent");
;             asm volatile("s_waitcnt vmcnt(0)" ::: "memory");
;             const unsigned og = xb_add(&bar[XB_TOP], 1u);
;             const unsigned tg = og / nx;
;             if (og + 1u == (tg + 1u) * nx) xb_add(&bar[XB_TOPGEN], 1u);
;             else XB_SPIN(xb_ld(&bar[XB_TOPGEN]) == tg, bar);
;             __builtin_amdgcn_fence(__ATOMIC_ACQUIRE, "agent");
;             xb_add(&bar[XB_XGEN(b.x)], 1u);
;             asm volatile("s_waitcnt vmcnt(0)" ::: "memory");
;         } else {
;             XB_SPIN(xb_ld(&bar[XB_XGEN(b.x)]) == gen, bar);
;             __builtin_amdgcn_fence(__ATOMIC_ACQUIRE, "agent");
;             asm volatile("s_waitcnt vmcnt(0)" ::: "memory");
;         }
;     }
;     __syncthreads();
.Lp3_wc_done:
	s_mov_b64 exec, s[98:99]
	s_barrier
	v_writelane_b32 v254, s30, 36
	s_nop 1
	v_writelane_b32 v254, s31, 37
	s_cbranch_execnz .LBB0_840
	s_branch .LBB0_990
